# attention row-max reductions (MLA and sliding-window, 6 sites): one v_max3 chain (16 ops) instead of max,max,max3 triples (24 ops); byte-size neutral; on top of v72
# speedup vs baseline: 1.0049x; 1.0012x over previous
.LBB0_360:
	s_nop 10
	v_max3_f32 v0, v81, v97, v82
	v_max3_f32 v0, v0, v98, v80
	v_max3_f32 v0, v0, v96, v83
	v_max3_f32 v0, v0, v99, v84
	v_max3_f32 v0, v0, v100, v85
	v_max3_f32 v0, v0, v101, v86
	v_max3_f32 v0, v0, v102, v87
	v_max3_f32 v0, v0, v103, v88
	v_max3_f32 v0, v0, v104, v89
	v_max3_f32 v0, v0, v105, v90
	v_max3_f32 v0, v0, v106, v91
	v_max3_f32 v0, v0, v107, v92
	v_max3_f32 v0, v0, v108, v93
	v_max3_f32 v0, v0, v109, v94
	v_max3_f32 v0, v0, v110, v95
	v_max_f32_e32 v0, v0, v111
	s_cmp_eq_u32 s57, 0
	s_cselect_b64 s[10:11], -1, 0
	s_cmp_lg_u32 s57, 0
	s_cbranch_scc0 .LBB0_368
	v_cmp_lt_f32_e32 vcc, s85, v0
	s_cmp_lg_u64 vcc, 0
	s_cselect_b64 s[36:37], -1, 0
	s_cbranch_execz .LBB0_369
	s_branch .LBB0_370

.LBB0_365:
	s_nop 10
	v_max3_f32 v0, v81, v97, v82
	v_max3_f32 v0, v0, v98, v80
	v_max3_f32 v0, v0, v96, v83
	v_max3_f32 v0, v0, v99, v84
	v_max3_f32 v0, v0, v100, v85
	v_max3_f32 v0, v0, v101, v86
	v_max3_f32 v0, v0, v102, v87
	v_max3_f32 v0, v0, v103, v88
	v_max3_f32 v0, v0, v104, v89
	v_max3_f32 v0, v0, v105, v90
	v_max3_f32 v0, v0, v106, v91
	v_max3_f32 v0, v0, v107, v92
	v_max3_f32 v0, v0, v108, v93
	v_max3_f32 v0, v0, v109, v94
	v_max3_f32 v0, v0, v110, v95
	v_max_f32_e64 v0, v0, v111
	v_cmp_lt_f32_e32 vcc, s85, v0
	s_cbranch_vccz .LBB0_367
	ds_bpermute_b32 v3, v178, v0
	s_waitcnt lgkmcnt(0)
	v_max3_f32 v0, v0, v3, 0
	v_exp_f32_e64 v4, -v0
	v_add_f32_e32 v165, v165, v0
	v_xor_b32_e32 v64, 0x80000000, v165
	v_pk_add_f32 v[80:81], v[80:81], v[0:1] op_sel_hi:[1,0] neg_lo:[0,1] neg_hi:[0,1]
	v_pk_add_f32 v[96:97], v[96:97], v[0:1] op_sel_hi:[1,0] neg_lo:[0,1] neg_hi:[0,1]
	v_pk_add_f32 v[82:83], v[82:83], v[0:1] op_sel_hi:[1,0] neg_lo:[0,1] neg_hi:[0,1]
	v_pk_add_f32 v[98:99], v[98:99], v[0:1] op_sel_hi:[1,0] neg_lo:[0,1] neg_hi:[0,1]
	v_pk_add_f32 v[84:85], v[84:85], v[0:1] op_sel_hi:[1,0] neg_lo:[0,1] neg_hi:[0,1]
	v_pk_add_f32 v[100:101], v[100:101], v[0:1] op_sel_hi:[1,0] neg_lo:[0,1] neg_hi:[0,1]
	v_pk_add_f32 v[86:87], v[86:87], v[0:1] op_sel_hi:[1,0] neg_lo:[0,1] neg_hi:[0,1]
	v_pk_add_f32 v[102:103], v[102:103], v[0:1] op_sel_hi:[1,0] neg_lo:[0,1] neg_hi:[0,1]
	v_pk_add_f32 v[88:89], v[88:89], v[0:1] op_sel_hi:[1,0] neg_lo:[0,1] neg_hi:[0,1]
	v_pk_add_f32 v[104:105], v[104:105], v[0:1] op_sel_hi:[1,0] neg_lo:[0,1] neg_hi:[0,1]
	v_pk_add_f32 v[90:91], v[90:91], v[0:1] op_sel_hi:[1,0] neg_lo:[0,1] neg_hi:[0,1]
	v_pk_add_f32 v[106:107], v[106:107], v[0:1] op_sel_hi:[1,0] neg_lo:[0,1] neg_hi:[0,1]
	v_pk_add_f32 v[92:93], v[92:93], v[0:1] op_sel_hi:[1,0] neg_lo:[0,1] neg_hi:[0,1]
	v_pk_add_f32 v[108:109], v[108:109], v[0:1] op_sel_hi:[1,0] neg_lo:[0,1] neg_hi:[0,1]
	v_pk_add_f32 v[94:95], v[94:95], v[0:1] op_sel_hi:[1,0] neg_lo:[0,1] neg_hi:[0,1]
	v_pk_add_f32 v[110:111], v[110:111], v[0:1] op_sel_hi:[1,0] neg_lo:[0,1] neg_hi:[0,1]
	v_pk_mul_f32 v[62:63], v[62:63], v[4:5] op_sel_hi:[1,0]
	v_pk_mul_f32 v[60:61], v[60:61], v[4:5] op_sel_hi:[1,0]
	v_pk_mul_f32 v[58:59], v[58:59], v[4:5] op_sel_hi:[1,0]
	v_pk_mul_f32 v[56:57], v[56:57], v[4:5] op_sel_hi:[1,0]
	v_pk_mul_f32 v[54:55], v[54:55], v[4:5] op_sel_hi:[1,0]
	v_pk_mul_f32 v[52:53], v[52:53], v[4:5] op_sel_hi:[1,0]
	v_pk_mul_f32 v[50:51], v[50:51], v[4:5] op_sel_hi:[1,0]
	v_pk_mul_f32 v[48:49], v[48:49], v[4:5] op_sel_hi:[1,0]
	v_pk_mul_f32 v[46:47], v[46:47], v[4:5] op_sel_hi:[1,0]
	v_pk_mul_f32 v[44:45], v[44:45], v[4:5] op_sel_hi:[1,0]
	v_pk_mul_f32 v[42:43], v[42:43], v[4:5] op_sel_hi:[1,0]
	v_pk_mul_f32 v[40:41], v[40:41], v[4:5] op_sel_hi:[1,0]
	v_pk_mul_f32 v[38:39], v[38:39], v[4:5] op_sel_hi:[1,0]
	v_pk_mul_f32 v[36:37], v[36:37], v[4:5] op_sel_hi:[1,0]
	v_pk_mul_f32 v[34:35], v[34:35], v[4:5] op_sel_hi:[1,0]
	v_pk_mul_f32 v[32:33], v[32:33], v[4:5] op_sel_hi:[1,0]
	v_mov_b32_e32 v65, v64
	v_mov_b32_e32 v66, v64
	v_mov_b32_e32 v67, v64
	v_mov_b32_e32 v68, v64
	v_mov_b32_e32 v69, v64
	v_mov_b32_e32 v70, v64
	v_mov_b32_e32 v71, v64
	v_mov_b32_e32 v72, v64
	v_mov_b32_e32 v73, v64
	v_mov_b32_e32 v74, v64
	v_mov_b32_e32 v75, v64
	v_mov_b32_e32 v76, v64
	v_mov_b32_e32 v77, v64
	v_mov_b32_e32 v78, v64
	v_mov_b32_e32 v79, v64
	v_mul_f32_e32 v6, v6, v4

.LBB0_398:
	s_nop 10
	v_max3_f32 v0, v81, v97, v82
	v_max3_f32 v0, v0, v98, v80
	v_max3_f32 v0, v0, v96, v83
	v_max3_f32 v0, v0, v99, v84
	v_max3_f32 v0, v0, v100, v85
	v_max3_f32 v0, v0, v101, v86
	v_max3_f32 v0, v0, v102, v87
	v_max3_f32 v0, v0, v103, v88
	v_max3_f32 v0, v0, v104, v89
	v_max3_f32 v0, v0, v105, v90
	v_max3_f32 v0, v0, v106, v91
	v_max3_f32 v0, v0, v107, v92
	v_max3_f32 v0, v0, v108, v93
	v_max3_f32 v0, v0, v109, v94
	v_max3_f32 v0, v0, v110, v95
	v_max_f32_e32 v0, v0, v111
	s_cmp_eq_u32 s37, 0
	s_cselect_b64 s[10:11], -1, 0
	s_cmp_lg_u32 s37, 0
	s_cbranch_scc0 .LBB0_406
	v_cmp_lt_f32_e32 vcc, s85, v0
	s_cmp_lg_u64 vcc, 0
	s_cselect_b64 s[16:17], -1, 0
	s_cbranch_execz .LBB0_407
	s_branch .LBB0_408

.LBB0_638:
	s_nop 10
	v_max3_f32 v0, v83, v67, v84
	v_max3_f32 v0, v0, v68, v82
	v_max3_f32 v0, v0, v66, v85
	v_max3_f32 v0, v0, v69, v86
	v_max3_f32 v0, v0, v70, v87
	v_max3_f32 v0, v0, v71, v88
	v_max3_f32 v0, v0, v72, v89
	v_max3_f32 v0, v0, v73, v90
	v_max3_f32 v0, v0, v74, v91
	v_max3_f32 v0, v0, v75, v92
	v_max3_f32 v0, v0, v76, v93
	v_max3_f32 v0, v0, v77, v94
	v_max3_f32 v0, v0, v78, v95
	v_max3_f32 v0, v0, v79, v96
	v_max3_f32 v0, v0, v80, v97
	v_max_f32_e64 v0, v0, v81
	v_cmp_lt_f32_e32 vcc, s85, v0
	s_cbranch_vccz .LBB0_640
	ds_bpermute_b32 v3, v143, v0
	s_waitcnt lgkmcnt(0)
	v_max3_f32 v0, v0, v3, 0
	v_exp_f32_e64 v4, -v0
	v_add_f32_e32 v145, v145, v0
	v_xor_b32_e32 v50, 0x80000000, v145
	v_pk_add_f32 v[82:83], v[82:83], v[0:1] op_sel_hi:[1,0] neg_lo:[0,1] neg_hi:[0,1]
	v_pk_add_f32 v[66:67], v[66:67], v[0:1] op_sel_hi:[1,0] neg_lo:[0,1] neg_hi:[0,1]
	v_pk_add_f32 v[84:85], v[84:85], v[0:1] op_sel_hi:[1,0] neg_lo:[0,1] neg_hi:[0,1]
	v_pk_add_f32 v[68:69], v[68:69], v[0:1] op_sel_hi:[1,0] neg_lo:[0,1] neg_hi:[0,1]
	v_pk_add_f32 v[86:87], v[86:87], v[0:1] op_sel_hi:[1,0] neg_lo:[0,1] neg_hi:[0,1]
	v_pk_add_f32 v[70:71], v[70:71], v[0:1] op_sel_hi:[1,0] neg_lo:[0,1] neg_hi:[0,1]
	v_pk_add_f32 v[88:89], v[88:89], v[0:1] op_sel_hi:[1,0] neg_lo:[0,1] neg_hi:[0,1]
	v_pk_add_f32 v[72:73], v[72:73], v[0:1] op_sel_hi:[1,0] neg_lo:[0,1] neg_hi:[0,1]
	v_pk_add_f32 v[90:91], v[90:91], v[0:1] op_sel_hi:[1,0] neg_lo:[0,1] neg_hi:[0,1]
	v_pk_add_f32 v[74:75], v[74:75], v[0:1] op_sel_hi:[1,0] neg_lo:[0,1] neg_hi:[0,1]
	v_pk_add_f32 v[92:93], v[92:93], v[0:1] op_sel_hi:[1,0] neg_lo:[0,1] neg_hi:[0,1]
	v_pk_add_f32 v[76:77], v[76:77], v[0:1] op_sel_hi:[1,0] neg_lo:[0,1] neg_hi:[0,1]
	v_pk_add_f32 v[94:95], v[94:95], v[0:1] op_sel_hi:[1,0] neg_lo:[0,1] neg_hi:[0,1]
	v_pk_add_f32 v[78:79], v[78:79], v[0:1] op_sel_hi:[1,0] neg_lo:[0,1] neg_hi:[0,1]
	v_pk_add_f32 v[96:97], v[96:97], v[0:1] op_sel_hi:[1,0] neg_lo:[0,1] neg_hi:[0,1]
	v_pk_add_f32 v[80:81], v[80:81], v[0:1] op_sel_hi:[1,0] neg_lo:[0,1] neg_hi:[0,1]
	v_pk_mul_f32 v[48:49], v[48:49], v[4:5] op_sel_hi:[1,0]
	v_pk_mul_f32 v[46:47], v[46:47], v[4:5] op_sel_hi:[1,0]
	v_pk_mul_f32 v[44:45], v[44:45], v[4:5] op_sel_hi:[1,0]
	v_pk_mul_f32 v[42:43], v[42:43], v[4:5] op_sel_hi:[1,0]
	v_pk_mul_f32 v[40:41], v[40:41], v[4:5] op_sel_hi:[1,0]
	v_pk_mul_f32 v[38:39], v[38:39], v[4:5] op_sel_hi:[1,0]
	v_pk_mul_f32 v[36:37], v[36:37], v[4:5] op_sel_hi:[1,0]
	v_pk_mul_f32 v[34:35], v[34:35], v[4:5] op_sel_hi:[1,0]
	v_pk_mul_f32 v[32:33], v[32:33], v[4:5] op_sel_hi:[1,0]
	v_pk_mul_f32 v[30:31], v[30:31], v[4:5] op_sel_hi:[1,0]
	v_pk_mul_f32 v[28:29], v[28:29], v[4:5] op_sel_hi:[1,0]
	v_pk_mul_f32 v[26:27], v[26:27], v[4:5] op_sel_hi:[1,0]
	v_pk_mul_f32 v[24:25], v[24:25], v[4:5] op_sel_hi:[1,0]
	v_pk_mul_f32 v[22:23], v[22:23], v[4:5] op_sel_hi:[1,0]
	v_pk_mul_f32 v[20:21], v[20:21], v[4:5] op_sel_hi:[1,0]
	v_pk_mul_f32 v[18:19], v[18:19], v[4:5] op_sel_hi:[1,0]
	v_mov_b32_e32 v51, v50
	v_mov_b32_e32 v52, v50
	v_mov_b32_e32 v53, v50
	v_mov_b32_e32 v54, v50
	v_mov_b32_e32 v55, v50
	v_mov_b32_e32 v56, v50
	v_mov_b32_e32 v57, v50
	v_mov_b32_e32 v58, v50
	v_mov_b32_e32 v59, v50
	v_mov_b32_e32 v60, v50
	v_mov_b32_e32 v61, v50
	v_mov_b32_e32 v62, v50
	v_mov_b32_e32 v63, v50
	v_mov_b32_e32 v64, v50
	v_mov_b32_e32 v65, v50
	v_mul_f32_e32 v148, v148, v4

.LBB0_644:
	s_nop 10
	v_max3_f32 v0, v83, v67, v84
	v_max3_f32 v0, v0, v68, v82
	v_max3_f32 v0, v0, v66, v85
	v_max3_f32 v0, v0, v69, v86
	v_max3_f32 v0, v0, v70, v87
	v_max3_f32 v0, v0, v71, v88
	v_max3_f32 v0, v0, v72, v89
	v_max3_f32 v0, v0, v73, v90
	v_max3_f32 v0, v0, v74, v91
	v_max3_f32 v0, v0, v75, v92
	v_max3_f32 v0, v0, v76, v93
	v_max3_f32 v0, v0, v77, v94
	v_max3_f32 v0, v0, v78, v95
	v_max3_f32 v0, v0, v79, v96
	v_max3_f32 v0, v0, v80, v97
	v_max_f32_e32 v0, v0, v81
	v_cmp_lt_f32_e32 vcc, s85, v0
	s_cbranch_vccz .LBB0_646
	ds_bpermute_b32 v2, v143, v0
	s_waitcnt lgkmcnt(0)
	v_max3_f32 v0, v0, v2, 0
	v_exp_f32_e64 v2, -v0
	v_add_f32_e32 v145, v145, v0
	v_xor_b32_e32 v50, 0x80000000, v145
	v_pk_add_f32 v[82:83], v[82:83], v[0:1] op_sel_hi:[1,0] neg_lo:[0,1] neg_hi:[0,1]
	v_pk_add_f32 v[66:67], v[66:67], v[0:1] op_sel_hi:[1,0] neg_lo:[0,1] neg_hi:[0,1]
	v_pk_add_f32 v[84:85], v[84:85], v[0:1] op_sel_hi:[1,0] neg_lo:[0,1] neg_hi:[0,1]
	v_pk_add_f32 v[68:69], v[68:69], v[0:1] op_sel_hi:[1,0] neg_lo:[0,1] neg_hi:[0,1]
	v_pk_add_f32 v[86:87], v[86:87], v[0:1] op_sel_hi:[1,0] neg_lo:[0,1] neg_hi:[0,1]
	v_pk_add_f32 v[70:71], v[70:71], v[0:1] op_sel_hi:[1,0] neg_lo:[0,1] neg_hi:[0,1]
	v_pk_add_f32 v[88:89], v[88:89], v[0:1] op_sel_hi:[1,0] neg_lo:[0,1] neg_hi:[0,1]
	v_pk_add_f32 v[72:73], v[72:73], v[0:1] op_sel_hi:[1,0] neg_lo:[0,1] neg_hi:[0,1]
	v_pk_add_f32 v[90:91], v[90:91], v[0:1] op_sel_hi:[1,0] neg_lo:[0,1] neg_hi:[0,1]
	v_pk_add_f32 v[74:75], v[74:75], v[0:1] op_sel_hi:[1,0] neg_lo:[0,1] neg_hi:[0,1]
	v_pk_add_f32 v[92:93], v[92:93], v[0:1] op_sel_hi:[1,0] neg_lo:[0,1] neg_hi:[0,1]
	v_pk_add_f32 v[76:77], v[76:77], v[0:1] op_sel_hi:[1,0] neg_lo:[0,1] neg_hi:[0,1]
	v_pk_add_f32 v[94:95], v[94:95], v[0:1] op_sel_hi:[1,0] neg_lo:[0,1] neg_hi:[0,1]
	v_pk_add_f32 v[78:79], v[78:79], v[0:1] op_sel_hi:[1,0] neg_lo:[0,1] neg_hi:[0,1]
	v_pk_add_f32 v[96:97], v[96:97], v[0:1] op_sel_hi:[1,0] neg_lo:[0,1] neg_hi:[0,1]
	v_pk_add_f32 v[80:81], v[80:81], v[0:1] op_sel_hi:[1,0] neg_lo:[0,1] neg_hi:[0,1]
	v_pk_mul_f32 v[48:49], v[48:49], v[2:3] op_sel_hi:[1,0]
	v_pk_mul_f32 v[46:47], v[46:47], v[2:3] op_sel_hi:[1,0]
	v_pk_mul_f32 v[44:45], v[44:45], v[2:3] op_sel_hi:[1,0]
	v_pk_mul_f32 v[42:43], v[42:43], v[2:3] op_sel_hi:[1,0]
	v_pk_mul_f32 v[40:41], v[40:41], v[2:3] op_sel_hi:[1,0]
	v_pk_mul_f32 v[38:39], v[38:39], v[2:3] op_sel_hi:[1,0]
	v_pk_mul_f32 v[36:37], v[36:37], v[2:3] op_sel_hi:[1,0]
	v_pk_mul_f32 v[34:35], v[34:35], v[2:3] op_sel_hi:[1,0]
	v_pk_mul_f32 v[32:33], v[32:33], v[2:3] op_sel_hi:[1,0]
	v_pk_mul_f32 v[30:31], v[30:31], v[2:3] op_sel_hi:[1,0]
	v_pk_mul_f32 v[28:29], v[28:29], v[2:3] op_sel_hi:[1,0]
	v_pk_mul_f32 v[26:27], v[26:27], v[2:3] op_sel_hi:[1,0]
	v_pk_mul_f32 v[24:25], v[24:25], v[2:3] op_sel_hi:[1,0]
	v_pk_mul_f32 v[22:23], v[22:23], v[2:3] op_sel_hi:[1,0]
	v_pk_mul_f32 v[20:21], v[20:21], v[2:3] op_sel_hi:[1,0]
	v_pk_mul_f32 v[18:19], v[18:19], v[2:3] op_sel_hi:[1,0]
	v_mov_b32_e32 v51, v50
	v_mov_b32_e32 v52, v50
	v_mov_b32_e32 v53, v50
	v_mov_b32_e32 v54, v50
	v_mov_b32_e32 v55, v50
	v_mov_b32_e32 v56, v50
	v_mov_b32_e32 v57, v50
	v_mov_b32_e32 v58, v50
	v_mov_b32_e32 v59, v50
	v_mov_b32_e32 v60, v50
	v_mov_b32_e32 v61, v50
	v_mov_b32_e32 v62, v50
	v_mov_b32_e32 v63, v50
	v_mov_b32_e32 v64, v50
	v_mov_b32_e32 v65, v50
	v_mul_f32_e32 v148, v148, v2
